# adds mLSTM-local MFMA chains pipelined (A fragments read 4 steps ahead) and PV V-fragment reads hoisted in mLSTM-out
# baseline (speedup 1.0000x reference)
.LBB0_1912:
	s_or_b64 exec, exec, s[54:55]
	s_waitcnt lgkmcnt(0)
	s_barrier
	ds_read_b32 v32, v126
	s_waitcnt vmcnt(7)
	v_lshlrev_b32_e32 v33, 16, v28
	v_and_b32_e32 v28, 0xffff0000, v28
	s_sub_i32 s0, s64, s17
	s_add_i32 s54, s16, s0
	s_waitcnt lgkmcnt(0)
	v_mul_f32_e32 v33, v32, v33
	v_cvt_pk_bf16_f32 v33, v33, v109
	v_mul_f32_e32 v28, v32, v28
	ds_write_b16 v128, v33
	s_waitcnt vmcnt(6)
	ds_write_b16 v128, v24 offset:34816
	v_cvt_pk_bf16_f32 v28, v28, v109
	ds_write_b16 v128, v28 offset:272
	ds_write_b16_d16_hi v128, v24 offset:35088
	v_lshlrev_b32_e32 v24, 16, v29
	v_mul_f32_e32 v24, v32, v24
	v_cvt_pk_bf16_f32 v24, v24, v109
	ds_write_b16 v128, v24 offset:544
	ds_write_b16 v128, v25 offset:35360
	v_and_b32_e32 v24, 0xffff0000, v29
	v_mul_f32_e32 v24, v32, v24
	v_cvt_pk_bf16_f32 v24, v24, v109
	ds_write_b16 v128, v24 offset:816
	ds_write_b16_d16_hi v128, v25 offset:35632
	v_lshlrev_b32_e32 v24, 16, v30
	v_mul_f32_e32 v24, v32, v24
	v_cvt_pk_bf16_f32 v24, v24, v109
	ds_write_b16 v128, v24 offset:1088
	ds_write_b16 v128, v26 offset:35904
	v_and_b32_e32 v24, 0xffff0000, v30
	v_mul_f32_e32 v24, v32, v24
	v_cvt_pk_bf16_f32 v24, v24, v109
	ds_write_b16 v128, v24 offset:1360
	ds_write_b16_d16_hi v128, v26 offset:36176
	v_lshlrev_b32_e32 v24, 16, v31
	v_mul_f32_e32 v24, v32, v24
	v_cvt_pk_bf16_f32 v24, v24, v109
	ds_write_b16 v128, v24 offset:1632
	ds_write_b16 v128, v27 offset:36448
	v_and_b32_e32 v24, 0xffff0000, v31
	v_mul_f32_e32 v24, v32, v24
	v_cvt_pk_bf16_f32 v24, v24, v109
	ds_write_b16 v129, v24
	ds_write_b16_d16_hi v129, v27 offset:34816
	ds_read_b32 v24, v126
	s_waitcnt vmcnt(5)
	v_lshlrev_b32_e32 v25, 16, v20
	v_and_b32_e32 v20, 0xffff0000, v20
	s_ashr_i32 s55, s54, 31
	s_lshl_b64 s[0:1], s[54:55], 16
	s_waitcnt lgkmcnt(0)
	v_mul_f32_e32 v25, v24, v25
	v_cvt_pk_bf16_f32 v25, v25, v109
	v_mul_f32_e32 v20, v24, v20
	ds_write_b16 v130, v25
	s_waitcnt vmcnt(4)
	ds_write_b16 v130, v16 offset:34816
	v_cvt_pk_bf16_f32 v20, v20, v109
	ds_write_b16 v130, v20 offset:272
	ds_write_b16_d16_hi v130, v16 offset:35088
	v_lshlrev_b32_e32 v16, 16, v21
	v_mul_f32_e32 v16, v24, v16
	v_cvt_pk_bf16_f32 v16, v16, v109
	ds_write_b16 v130, v16 offset:544
	ds_write_b16 v130, v17 offset:35360
	v_and_b32_e32 v16, 0xffff0000, v21
	v_mul_f32_e32 v16, v24, v16
	v_cvt_pk_bf16_f32 v16, v16, v109
	ds_write_b16 v130, v16 offset:816
	ds_write_b16_d16_hi v130, v17 offset:35632
	v_lshlrev_b32_e32 v16, 16, v22
	v_mul_f32_e32 v16, v24, v16
	v_cvt_pk_bf16_f32 v16, v16, v109
	ds_write_b16 v130, v16 offset:1088
	ds_write_b16 v130, v18 offset:35904
	v_and_b32_e32 v16, 0xffff0000, v22
	v_mul_f32_e32 v16, v24, v16
	v_cvt_pk_bf16_f32 v16, v16, v109
	ds_write_b16 v130, v16 offset:1360
	ds_write_b16_d16_hi v130, v18 offset:36176
	v_lshlrev_b32_e32 v16, 16, v23
	v_mul_f32_e32 v16, v24, v16
	v_cvt_pk_bf16_f32 v16, v16, v109
	ds_write_b16 v130, v16 offset:1632
	ds_write_b16 v130, v19 offset:36448
	v_and_b32_e32 v16, 0xffff0000, v23
	v_mul_f32_e32 v16, v24, v16
	v_cvt_pk_bf16_f32 v16, v16, v109
	ds_write_b16 v131, v16
	ds_write_b16_d16_hi v131, v19 offset:34816
	ds_read_b32 v16, v126
	s_waitcnt vmcnt(3)
	v_lshlrev_b32_e32 v17, 16, v12
	v_and_b32_e32 v12, 0xffff0000, v12
	s_add_u32 s66, s94, s0
	s_addc_u32 s67, s95, s1
	s_waitcnt lgkmcnt(0)
	v_mul_f32_e32 v17, v16, v17
	v_cvt_pk_bf16_f32 v17, v17, v109
	v_mul_f32_e32 v12, v16, v12
	ds_write_b16 v133, v17
	s_waitcnt vmcnt(2)
	ds_write_b16 v133, v8 offset:34816
	v_cvt_pk_bf16_f32 v12, v12, v109
	ds_write_b16 v133, v12 offset:272
	ds_write_b16_d16_hi v133, v8 offset:35088
	v_lshlrev_b32_e32 v8, 16, v13
	v_mul_f32_e32 v8, v16, v8
	v_cvt_pk_bf16_f32 v8, v8, v109
	ds_write_b16 v133, v8 offset:544
	ds_write_b16 v133, v9 offset:35360
	v_and_b32_e32 v8, 0xffff0000, v13
	v_mul_f32_e32 v8, v16, v8
	v_cvt_pk_bf16_f32 v8, v8, v109
	ds_write_b16 v133, v8 offset:816
	ds_write_b16_d16_hi v133, v9 offset:35632
	v_lshlrev_b32_e32 v8, 16, v14
	v_mul_f32_e32 v8, v16, v8
	v_cvt_pk_bf16_f32 v8, v8, v109
	ds_write_b16 v133, v8 offset:1088
	ds_write_b16 v133, v10 offset:35904
	v_and_b32_e32 v8, 0xffff0000, v14
	v_mul_f32_e32 v8, v16, v8
	v_cvt_pk_bf16_f32 v8, v8, v109
	ds_write_b16 v133, v8 offset:1360
	ds_write_b16_d16_hi v133, v10 offset:36176
	v_lshlrev_b32_e32 v8, 16, v15
	v_mul_f32_e32 v8, v16, v8
	v_cvt_pk_bf16_f32 v8, v8, v109
	ds_write_b16 v133, v8 offset:1632
	ds_write_b16 v133, v11 offset:36448
	v_and_b32_e32 v8, 0xffff0000, v15
	v_mul_f32_e32 v8, v16, v8
	v_cvt_pk_bf16_f32 v8, v8, v109
	ds_write_b16 v134, v8
	ds_write_b16_d16_hi v134, v11 offset:34816
	ds_read_b32 v8, v126
	s_waitcnt vmcnt(1)
	v_lshlrev_b32_e32 v9, 16, v4
	v_and_b32_e32 v4, 0xffff0000, v4
	s_waitcnt lgkmcnt(0)
	v_mul_f32_e32 v9, v8, v9
	v_cvt_pk_bf16_f32 v9, v9, v109
	v_mul_f32_e32 v4, v8, v4
	ds_write_b16 v135, v9
	s_waitcnt vmcnt(0)
	ds_write_b16 v135, v0 offset:34816
	v_cvt_pk_bf16_f32 v4, v4, v109
	ds_write_b16 v135, v4 offset:272
	ds_write_b16_d16_hi v135, v0 offset:35088
	v_lshlrev_b32_e32 v0, 16, v5
	v_mul_f32_e32 v0, v8, v0
	v_cvt_pk_bf16_f32 v0, v0, v109
	ds_write_b16 v135, v0 offset:544
	ds_write_b16 v135, v1 offset:35360
	v_and_b32_e32 v0, 0xffff0000, v5
	v_mul_f32_e32 v0, v8, v0
	v_cvt_pk_bf16_f32 v0, v0, v109
	ds_write_b16 v135, v0 offset:816
	ds_write_b16_d16_hi v135, v1 offset:35632
	v_lshlrev_b32_e32 v0, 16, v6
	v_mul_f32_e32 v0, v8, v0
	v_cvt_pk_bf16_f32 v0, v0, v109
	ds_write_b16 v135, v0 offset:1088
	ds_write_b16 v135, v2 offset:35904
	v_and_b32_e32 v0, 0xffff0000, v6
	v_mul_f32_e32 v0, v8, v0
	v_cvt_pk_bf16_f32 v0, v0, v109
	ds_write_b16 v135, v0 offset:1360
	ds_write_b16_d16_hi v135, v2 offset:36176
	v_lshlrev_b32_e32 v0, 16, v7
	v_mul_f32_e32 v0, v8, v0
	v_cvt_pk_bf16_f32 v0, v0, v109
	ds_write_b16 v135, v0 offset:1632
	ds_write_b16 v135, v3 offset:36448
	v_and_b32_e32 v0, 0xffff0000, v7
	v_mul_f32_e32 v0, v8, v0
	v_cvt_pk_bf16_f32 v0, v0, v109
	ds_write_b16 v136, v0
	ds_write_b16_d16_hi v136, v3 offset:34816
	s_waitcnt lgkmcnt(0)
	s_barrier
	ds_read_b128 v[44:47], v127
	ds_read_b128 v[40:43], v127 offset:32
	ds_read_b128 v[36:39], v127 offset:64
	ds_read_b128 v[32:35], v127 offset:96
	ds_read_b128 v[28:31], v127 offset:128
	ds_read_b128 v[24:27], v127 offset:160
	ds_read_b128 v[20:23], v127 offset:192
	ds_read_b128 v[16:19], v127 offset:224
	ds_read_b128 v[0:3], v138 offset:34816
	ds_read_b128 v[160:163], v138 offset:34848
	ds_read_b128 v[164:167], v138 offset:34880
	ds_read_b128 v[168:171], v138 offset:34912
	ds_read_b128 v[172:175], v138 offset:34944
	s_waitcnt lgkmcnt(4)
	v_mfma_f32_32x32x16_bf16 v[0:15], v[0:3], v[44:47], 0
	ds_read_b128 v[176:179], v138 offset:34976
	s_waitcnt lgkmcnt(4)
	v_mfma_f32_32x32x16_bf16 v[0:15], v[160:163], v[40:43], v[0:15]
	ds_read_b128 v[180:183], v138 offset:35008
	s_waitcnt lgkmcnt(4)
	v_mfma_f32_32x32x16_bf16 v[0:15], v[164:167], v[36:39], v[0:15]
	ds_read_b128 v[184:187], v138 offset:35040
	s_waitcnt lgkmcnt(4)
	v_mfma_f32_32x32x16_bf16 v[0:15], v[168:171], v[32:35], v[0:15]
	s_waitcnt lgkmcnt(3)
	v_mfma_f32_32x32x16_bf16 v[0:15], v[172:175], v[28:31], v[0:15]
	s_waitcnt lgkmcnt(2)
	v_mfma_f32_32x32x16_bf16 v[0:15], v[176:179], v[24:27], v[0:15]
	s_waitcnt lgkmcnt(1)
	v_mfma_f32_32x32x16_bf16 v[0:15], v[180:183], v[20:23], v[0:15]
	s_waitcnt lgkmcnt(0)
	v_mfma_f32_32x32x16_bf16 v[0:15], v[184:187], v[16:19], v[0:15]
	v_lshl_add_u64 v[142:143], v[52:53], 2, s[66:67]
	s_nop 10
	global_store_dword v[142:143], v0, off
	v_lshl_add_u64 v[142:143], v[104:105], 2, s[66:67]
	global_store_dword v[142:143], v1, off offset:512
	global_store_dword v[142:143], v2, off offset:1024
	global_store_dword v[142:143], v3, off offset:1536
	v_lshl_add_u64 v[0:1], v[54:55], 2, s[66:67]
	global_store_dword v[0:1], v4, off
	v_lshl_add_u64 v[0:1], v[56:57], 2, s[66:67]
	global_store_dword v[0:1], v5, off
	v_lshl_add_u64 v[0:1], v[58:59], 2, s[66:67]
	global_store_dword v[0:1], v6, off
	v_lshl_add_u64 v[0:1], v[60:61], 2, s[66:67]
	global_store_dword v[0:1], v7, off
	v_lshl_add_u64 v[0:1], v[62:63], 2, s[66:67]
	global_store_dword v[0:1], v8, off
	v_lshl_add_u64 v[0:1], v[64:65], 2, s[66:67]
	global_store_dword v[0:1], v9, off
	v_lshl_add_u64 v[0:1], v[66:67], 2, s[66:67]
	global_store_dword v[0:1], v10, off
	v_lshl_add_u64 v[0:1], v[68:69], 2, s[66:67]
	global_store_dword v[0:1], v11, off
	v_lshl_add_u64 v[0:1], v[70:71], 2, s[66:67]
	global_store_dword v[0:1], v12, off
	v_lshl_add_u64 v[0:1], v[72:73], 2, s[66:67]
	global_store_dword v[0:1], v13, off
	v_lshl_add_u64 v[0:1], v[74:75], 2, s[66:67]
	global_store_dword v[0:1], v14, off
	v_lshl_add_u64 v[0:1], v[76:77], 2, s[66:67]
	global_store_dword v[0:1], v15, off
	ds_read_b128 v[0:3], v139 offset:34816
	ds_read_b128 v[160:163], v139 offset:34848
	ds_read_b128 v[164:167], v139 offset:34880
	ds_read_b128 v[168:171], v139 offset:34912
	ds_read_b128 v[172:175], v139 offset:34944
	s_waitcnt lgkmcnt(4)
	v_mfma_f32_32x32x16_bf16 v[0:15], v[0:3], v[44:47], 0
	ds_read_b128 v[176:179], v139 offset:34976
	s_waitcnt lgkmcnt(4)
	v_mfma_f32_32x32x16_bf16 v[0:15], v[160:163], v[40:43], v[0:15]
	ds_read_b128 v[180:183], v139 offset:35008
	s_waitcnt lgkmcnt(4)
	v_mfma_f32_32x32x16_bf16 v[0:15], v[164:167], v[36:39], v[0:15]
	ds_read_b128 v[184:187], v139 offset:35040
	s_waitcnt lgkmcnt(4)
	v_mfma_f32_32x32x16_bf16 v[0:15], v[168:171], v[32:35], v[0:15]
	s_waitcnt lgkmcnt(3)
	v_mfma_f32_32x32x16_bf16 v[0:15], v[172:175], v[28:31], v[0:15]
	s_waitcnt lgkmcnt(2)
	v_mfma_f32_32x32x16_bf16 v[0:15], v[176:179], v[24:27], v[0:15]
	s_waitcnt lgkmcnt(1)
	v_mfma_f32_32x32x16_bf16 v[0:15], v[180:183], v[20:23], v[0:15]
	s_waitcnt lgkmcnt(0)
	v_mfma_f32_32x32x16_bf16 v[0:15], v[184:187], v[16:19], v[0:15]
	v_lshl_add_u64 v[16:17], v[78:79], 2, s[66:67]
	s_nop 10
	global_store_dword v[16:17], v0, off
	v_lshl_add_u64 v[16:17], v[106:107], 2, s[66:67]
	global_store_dword v[16:17], v1, off offset:512
	global_store_dword v[16:17], v2, off offset:1024
	global_store_dword v[16:17], v3, off offset:1536
	v_lshl_add_u64 v[0:1], v[80:81], 2, s[66:67]
	global_store_dword v[0:1], v4, off
	v_lshl_add_u64 v[0:1], v[82:83], 2, s[66:67]
	global_store_dword v[0:1], v5, off
	v_lshl_add_u64 v[0:1], v[84:85], 2, s[66:67]
	global_store_dword v[0:1], v6, off
	v_lshl_add_u64 v[0:1], v[86:87], 2, s[66:67]
	global_store_dword v[0:1], v7, off
	v_lshl_add_u64 v[0:1], v[88:89], 2, s[66:67]
	global_store_dword v[0:1], v8, off
	v_lshl_add_u64 v[0:1], v[90:91], 2, s[66:67]
	global_store_dword v[0:1], v9, off
	v_lshl_add_u64 v[0:1], v[92:93], 2, s[66:67]
	global_store_dword v[0:1], v10, off
	v_lshl_add_u64 v[0:1], v[94:95], 2, s[66:67]
	global_store_dword v[0:1], v11, off
	v_lshl_add_u64 v[0:1], v[96:97], 2, s[66:67]
	global_store_dword v[0:1], v12, off
	v_lshl_add_u64 v[0:1], v[98:99], 2, s[66:67]
	global_store_dword v[0:1], v13, off
	v_lshl_add_u64 v[0:1], v[100:101], 2, s[66:67]
	global_store_dword v[0:1], v14, off
	v_lshl_add_u64 v[0:1], v[102:103], 2, s[66:67]
	global_store_dword v[0:1], v15, off
	s_and_saveexec_b64 s[66:67], s[4:5]
	s_cbranch_execz .LBB0_1894
	ds_read_b128 v[0:3], v140
	ds_read_b128 v[4:7], v140 offset:16
	ds_read_b128 v[8:11], v140 offset:32
	ds_read_b128 v[12:15], v140 offset:48
	s_lshl_b64 s[0:1], s[54:55], 9
	s_waitcnt lgkmcnt(3)
	v_lshlrev_b32_e32 v16, 16, v0
	v_and_b32_e32 v0, 0xffff0000, v0
	v_add_f32_e32 v16, 0, v16
	v_add_f32_e32 v0, v16, v0
	v_lshlrev_b32_e32 v16, 16, v1
	v_add_f32_e32 v0, v0, v16
	v_and_b32_e32 v1, 0xffff0000, v1
	v_add_f32_e32 v0, v0, v1
	v_lshlrev_b32_e32 v1, 16, v2
	v_add_f32_e32 v0, v0, v1
	v_and_b32_e32 v1, 0xffff0000, v2
	v_add_f32_e32 v0, v0, v1
	v_lshlrev_b32_e32 v1, 16, v3
	v_add_f32_e32 v0, v0, v1
	v_and_b32_e32 v1, 0xffff0000, v3
	v_add_f32_e32 v0, v0, v1
	s_waitcnt lgkmcnt(2)
	v_lshlrev_b32_e32 v1, 16, v4
	v_add_f32_e32 v0, v0, v1
	v_and_b32_e32 v1, 0xffff0000, v4
	v_add_f32_e32 v0, v0, v1
	v_lshlrev_b32_e32 v1, 16, v5
	v_add_f32_e32 v0, v0, v1
	v_and_b32_e32 v1, 0xffff0000, v5
	v_add_f32_e32 v0, v0, v1
	v_lshlrev_b32_e32 v1, 16, v6
	v_add_f32_e32 v0, v0, v1
	v_and_b32_e32 v1, 0xffff0000, v6
	v_add_f32_e32 v0, v0, v1
	v_lshlrev_b32_e32 v1, 16, v7
	v_add_f32_e32 v0, v0, v1
	v_and_b32_e32 v1, 0xffff0000, v7
	v_add_f32_e32 v0, v0, v1
	s_waitcnt lgkmcnt(1)
	v_lshlrev_b32_e32 v1, 16, v8
	v_add_f32_e32 v0, v0, v1
	v_and_b32_e32 v1, 0xffff0000, v8
	v_add_f32_e32 v0, v0, v1
	v_lshlrev_b32_e32 v1, 16, v9
	v_add_f32_e32 v0, v0, v1
	v_and_b32_e32 v1, 0xffff0000, v9
	v_add_f32_e32 v0, v0, v1
	v_lshlrev_b32_e32 v1, 16, v10
	v_add_f32_e32 v0, v0, v1
	v_and_b32_e32 v1, 0xffff0000, v10
	v_add_f32_e32 v0, v0, v1
	v_lshlrev_b32_e32 v1, 16, v11
	v_add_f32_e32 v0, v0, v1
	v_and_b32_e32 v1, 0xffff0000, v11
	v_add_f32_e32 v0, v0, v1
	s_waitcnt lgkmcnt(0)
	v_lshlrev_b32_e32 v1, 16, v12
	v_add_f32_e32 v0, v0, v1
	v_and_b32_e32 v1, 0xffff0000, v12
	v_add_f32_e32 v0, v0, v1
	v_lshlrev_b32_e32 v1, 16, v13
	v_add_f32_e32 v0, v0, v1
	v_and_b32_e32 v1, 0xffff0000, v13
	v_add_f32_e32 v0, v0, v1
	v_lshlrev_b32_e32 v1, 16, v14
	v_add_f32_e32 v0, v0, v1
	v_and_b32_e32 v1, 0xffff0000, v14
	v_add_f32_e32 v4, v0, v1
	ds_read_b128 v[0:3], v140 offset:64
	v_lshlrev_b32_e32 v5, 16, v15
	v_add_f32_e32 v4, v4, v5
	v_and_b32_e32 v5, 0xffff0000, v15
	v_add_f32_e32 v8, v4, v5
	ds_read_b128 v[4:7], v140 offset:80
	s_waitcnt lgkmcnt(1)
	v_lshlrev_b32_e32 v9, 16, v0
	v_add_f32_e32 v8, v8, v9
	v_and_b32_e32 v0, 0xffff0000, v0
	v_add_f32_e32 v0, v8, v0
	v_lshlrev_b32_e32 v8, 16, v1
	v_add_f32_e32 v0, v0, v8
	v_and_b32_e32 v1, 0xffff0000, v1
	v_add_f32_e32 v0, v0, v1
	v_lshlrev_b32_e32 v1, 16, v2
	v_add_f32_e32 v0, v0, v1
	v_and_b32_e32 v1, 0xffff0000, v2
	v_add_f32_e32 v0, v0, v1
	v_lshlrev_b32_e32 v1, 16, v3
	v_add_f32_e32 v0, v0, v1
	v_and_b32_e32 v1, 0xffff0000, v3
	v_add_f32_e32 v0, v0, v1
	s_waitcnt lgkmcnt(0)
	v_lshlrev_b32_e32 v1, 16, v4
	v_add_f32_e32 v0, v0, v1
	v_and_b32_e32 v1, 0xffff0000, v4
	v_add_f32_e32 v0, v0, v1
	v_lshlrev_b32_e32 v1, 16, v5
	v_add_f32_e32 v0, v0, v1
	v_and_b32_e32 v1, 0xffff0000, v5
	v_add_f32_e32 v0, v0, v1
	v_lshlrev_b32_e32 v1, 16, v6
	v_add_f32_e32 v0, v0, v1
	v_and_b32_e32 v1, 0xffff0000, v6
	v_add_f32_e32 v4, v0, v1
	ds_read_b128 v[0:3], v140 offset:96
	v_lshlrev_b32_e32 v5, 16, v7
	v_add_f32_e32 v4, v4, v5
	v_and_b32_e32 v5, 0xffff0000, v7
	v_add_f32_e32 v8, v4, v5
	ds_read_b128 v[4:7], v140 offset:112
	s_waitcnt lgkmcnt(1)
	v_lshlrev_b32_e32 v9, 16, v0
	v_add_f32_e32 v8, v8, v9
	v_and_b32_e32 v0, 0xffff0000, v0
	v_add_f32_e32 v0, v8, v0
	v_lshlrev_b32_e32 v8, 16, v1
	v_add_f32_e32 v0, v0, v8
	v_and_b32_e32 v1, 0xffff0000, v1
	v_add_f32_e32 v0, v0, v1
	v_lshlrev_b32_e32 v1, 16, v2
	v_add_f32_e32 v0, v0, v1
	v_and_b32_e32 v1, 0xffff0000, v2
	v_add_f32_e32 v0, v0, v1
	v_lshlrev_b32_e32 v1, 16, v3
	v_add_f32_e32 v0, v0, v1
	v_and_b32_e32 v1, 0xffff0000, v3
	v_add_f32_e32 v0, v0, v1
	s_waitcnt lgkmcnt(0)
	v_lshlrev_b32_e32 v1, 16, v4
	v_add_f32_e32 v0, v0, v1
	v_and_b32_e32 v1, 0xffff0000, v4
	v_add_f32_e32 v0, v0, v1
	v_lshlrev_b32_e32 v1, 16, v5
	v_add_f32_e32 v0, v0, v1
	v_and_b32_e32 v1, 0xffff0000, v5
	v_add_f32_e32 v0, v0, v1
	v_lshlrev_b32_e32 v1, 16, v6
	v_add_f32_e32 v0, v0, v1
	v_and_b32_e32 v1, 0xffff0000, v6
	v_add_f32_e32 v4, v0, v1
	ds_read_b128 v[0:3], v140 offset:128
	v_lshlrev_b32_e32 v5, 16, v7
	v_add_f32_e32 v4, v4, v5
	v_and_b32_e32 v5, 0xffff0000, v7
	v_add_f32_e32 v8, v4, v5
	ds_read_b128 v[4:7], v140 offset:144
	s_waitcnt lgkmcnt(1)
	v_lshlrev_b32_e32 v9, 16, v0
	v_add_f32_e32 v8, v8, v9
	v_and_b32_e32 v0, 0xffff0000, v0
	v_add_f32_e32 v0, v8, v0
	v_lshlrev_b32_e32 v8, 16, v1
	v_add_f32_e32 v0, v0, v8
	v_and_b32_e32 v1, 0xffff0000, v1
	v_add_f32_e32 v0, v0, v1
	v_lshlrev_b32_e32 v1, 16, v2
	v_add_f32_e32 v0, v0, v1
	v_and_b32_e32 v1, 0xffff0000, v2
	v_add_f32_e32 v0, v0, v1
	v_lshlrev_b32_e32 v1, 16, v3
	v_add_f32_e32 v0, v0, v1
	v_and_b32_e32 v1, 0xffff0000, v3
	v_add_f32_e32 v0, v0, v1
	s_waitcnt lgkmcnt(0)
	v_lshlrev_b32_e32 v1, 16, v4
	v_add_f32_e32 v0, v0, v1
	v_and_b32_e32 v1, 0xffff0000, v4
	v_add_f32_e32 v0, v0, v1
	v_lshlrev_b32_e32 v1, 16, v5
	v_add_f32_e32 v0, v0, v1
	v_and_b32_e32 v1, 0xffff0000, v5
	v_add_f32_e32 v0, v0, v1
	v_lshlrev_b32_e32 v1, 16, v6
	v_add_f32_e32 v0, v0, v1
	v_and_b32_e32 v1, 0xffff0000, v6
	v_add_f32_e32 v4, v0, v1
	ds_read_b128 v[0:3], v140 offset:160
	v_lshlrev_b32_e32 v5, 16, v7
	v_add_f32_e32 v4, v4, v5
	v_and_b32_e32 v5, 0xffff0000, v7
	v_add_f32_e32 v8, v4, v5
	ds_read_b128 v[4:7], v140 offset:176
	s_waitcnt lgkmcnt(1)
	v_lshlrev_b32_e32 v9, 16, v0
	v_add_f32_e32 v8, v8, v9
	v_and_b32_e32 v0, 0xffff0000, v0
	v_add_f32_e32 v0, v8, v0
	v_lshlrev_b32_e32 v8, 16, v1
	v_add_f32_e32 v0, v0, v8
	v_and_b32_e32 v1, 0xffff0000, v1
	v_add_f32_e32 v0, v0, v1
	v_lshlrev_b32_e32 v1, 16, v2
	v_add_f32_e32 v0, v0, v1
	v_and_b32_e32 v1, 0xffff0000, v2
	v_add_f32_e32 v0, v0, v1
	v_lshlrev_b32_e32 v1, 16, v3
	v_add_f32_e32 v0, v0, v1
	v_and_b32_e32 v1, 0xffff0000, v3
	v_add_f32_e32 v0, v0, v1
	s_waitcnt lgkmcnt(0)
	v_lshlrev_b32_e32 v1, 16, v4
	v_add_f32_e32 v0, v0, v1
	v_and_b32_e32 v1, 0xffff0000, v4
	v_add_f32_e32 v0, v0, v1
	v_lshlrev_b32_e32 v1, 16, v5
	v_add_f32_e32 v0, v0, v1
	v_and_b32_e32 v1, 0xffff0000, v5
	v_add_f32_e32 v0, v0, v1
	v_lshlrev_b32_e32 v1, 16, v6
	v_add_f32_e32 v0, v0, v1
	v_and_b32_e32 v1, 0xffff0000, v6
	v_add_f32_e32 v4, v0, v1
	ds_read_b128 v[0:3], v140 offset:192
	v_lshlrev_b32_e32 v5, 16, v7
	v_add_f32_e32 v4, v4, v5
	v_and_b32_e32 v5, 0xffff0000, v7
	v_add_f32_e32 v8, v4, v5
	ds_read_b128 v[4:7], v140 offset:208
	s_waitcnt lgkmcnt(1)
	v_lshlrev_b32_e32 v9, 16, v0
	v_add_f32_e32 v8, v8, v9
	v_and_b32_e32 v0, 0xffff0000, v0
	v_add_f32_e32 v0, v8, v0
	v_lshlrev_b32_e32 v8, 16, v1
	v_add_f32_e32 v0, v0, v8
	v_and_b32_e32 v1, 0xffff0000, v1
	v_add_f32_e32 v0, v0, v1
	v_lshlrev_b32_e32 v1, 16, v2
	v_add_f32_e32 v0, v0, v1
	v_and_b32_e32 v1, 0xffff0000, v2
	v_add_f32_e32 v0, v0, v1
	v_lshlrev_b32_e32 v1, 16, v3
	v_add_f32_e32 v0, v0, v1
	v_and_b32_e32 v1, 0xffff0000, v3
	v_add_f32_e32 v0, v0, v1
	s_waitcnt lgkmcnt(0)
	v_lshlrev_b32_e32 v1, 16, v4
	v_add_f32_e32 v0, v0, v1
	v_and_b32_e32 v1, 0xffff0000, v4
	v_add_f32_e32 v0, v0, v1
	v_lshlrev_b32_e32 v1, 16, v5
	v_add_f32_e32 v0, v0, v1
	v_and_b32_e32 v1, 0xffff0000, v5
	v_add_f32_e32 v0, v0, v1
	v_lshlrev_b32_e32 v1, 16, v6
	v_add_f32_e32 v0, v0, v1
	v_and_b32_e32 v1, 0xffff0000, v6
	v_add_f32_e32 v4, v0, v1
	ds_read_b128 v[0:3], v140 offset:224
	v_lshlrev_b32_e32 v5, 16, v7
	v_add_f32_e32 v4, v4, v5
	v_and_b32_e32 v5, 0xffff0000, v7
	v_add_f32_e32 v8, v4, v5
	ds_read_b128 v[4:7], v140 offset:240
	s_waitcnt lgkmcnt(1)
	v_lshlrev_b32_e32 v9, 16, v0
	v_add_f32_e32 v8, v8, v9
	v_and_b32_e32 v0, 0xffff0000, v0
	v_add_f32_e32 v0, v8, v0
	v_lshlrev_b32_e32 v8, 16, v1
	v_add_f32_e32 v0, v0, v8
	v_and_b32_e32 v1, 0xffff0000, v1
	v_add_f32_e32 v0, v0, v1
	v_lshlrev_b32_e32 v1, 16, v2
	v_add_f32_e32 v0, v0, v1
	v_and_b32_e32 v1, 0xffff0000, v2
	v_add_f32_e32 v0, v0, v1
	v_lshlrev_b32_e32 v1, 16, v3
	v_add_f32_e32 v0, v0, v1
	v_and_b32_e32 v1, 0xffff0000, v3
	v_add_f32_e32 v0, v0, v1
	s_waitcnt lgkmcnt(0)
	v_lshlrev_b32_e32 v1, 16, v4
	v_add_f32_e32 v0, v0, v1
	v_and_b32_e32 v1, 0xffff0000, v4
	v_add_f32_e32 v0, v0, v1
	v_lshlrev_b32_e32 v1, 16, v5
	v_add_f32_e32 v0, v0, v1
	v_and_b32_e32 v1, 0xffff0000, v5
	v_add_f32_e32 v0, v0, v1
	v_lshlrev_b32_e32 v1, 16, v6
	v_add_f32_e32 v0, v0, v1
	v_and_b32_e32 v1, 0xffff0000, v6
	v_add_f32_e32 v0, v0, v1
	v_lshlrev_b32_e32 v1, 16, v7
	v_add_f32_e32 v0, v0, v1
	v_and_b32_e32 v1, 0xffff0000, v7
	v_add_f32_e32 v2, v0, v1
	v_lshl_add_u64 v[0:1], v[50:51], 0, s[0:1]
	global_store_dword v[0:1], v2, off
	s_branch .LBB0_1894

.LBB0_2209:
	s_or_b64 exec, exec, s[20:21]
	v_add_u32_e32 v217, v50, v104
	v_add_u32_e32 v189, 0x11000, v217
	ds_read_b128 v[234:237], v189
	ds_read_b128 v[238:241], v189 offset:32
	v_add_u32_e32 v189, 0x13200, v217
	ds_read_b128 v[242:245], v189
	ds_read_b128 v[246:249], v189 offset:32
	v_add_f32_e32 v45, v51, v52
	v_add_f32_e32 v45, v45, v53
	v_add_f32_e32 v45, v45, v32
	v_add_f32_e32 v45, v45, v34
	v_add_f32_e32 v45, v45, v33
	v_add_f32_e32 v45, v45, v36
	v_add_f32_e32 v45, v45, v35
	v_add_f32_e32 v45, v45, v38
	v_add_f32_e32 v45, v45, v37
	v_add_f32_e32 v45, v45, v40
	v_cvt_pk_bf16_f32 v52, v52, v53
	v_cvt_pk_bf16_f32 v53, v32, v34
	v_cvt_pk_bf16_f32 v54, v33, v36
	v_cvt_pk_bf16_f32 v55, v35, v38
	v_cvt_pk_bf16_f32 v32, v37, v40
	v_add_u32_e32 v40, v50, v104
	v_add_f32_e32 v45, v45, v39
	v_permlane32_swap_b32_e32 v52, v54
	v_permlane32_swap_b32_e32 v53, v55
	v_cvt_pk_bf16_f32 v33, v39, v42
	v_cvt_pk_bf16_f32 v34, v41, v56
	v_cvt_pk_bf16_f32 v35, v44, v43
	s_waitcnt lgkmcnt(3)
	v_mfma_f32_32x32x16_bf16 v[16:31], v[52:55], v[234:237], v[16:31]
	v_permlane32_swap_b32_e32 v32, v34
	v_permlane32_swap_b32_e32 v33, v35
	v_add_f32_e32 v45, v45, v42
	s_waitcnt lgkmcnt(2)
	v_mfma_f32_32x32x16_bf16 v[16:31], v[32:35], v[238:241], v[16:31]
	v_add_f32_e32 v45, v45, v41
	v_add_f32_e32 v45, v45, v56
	v_add_f32_e32 v45, v45, v44
	s_add_i32 s23, s23, 32
	s_addk_i32 s22, 0x80
	s_waitcnt lgkmcnt(1)
	v_mfma_f32_32x32x16_bf16 v[0:15], v[52:55], v[242:245], v[0:15]
	v_add_f32_e32 v51, v45, v43
	v_add_u32_e32 v50, 64, v50
	v_add_u32_e32 v49, 0x2200, v49
	s_cmp_eq_u32 s88, s23
	s_waitcnt lgkmcnt(0)
	v_mfma_f32_32x32x16_bf16 v[0:15], v[32:35], v[246:249], v[0:15]
	s_cbranch_scc1 .LBB0_2242

.LBB0_4646:
	s_or_b64 exec, exec, s[6:7]
	s_waitcnt lgkmcnt(0)
	s_barrier
	ds_read_b32 v32, v126
	s_waitcnt vmcnt(7)
	v_lshlrev_b32_e32 v33, 16, v28
	v_and_b32_e32 v28, 0xffff0000, v28
	s_sub_i32 s4, s4, s19
	s_add_i32 s6, s18, s4
	s_waitcnt lgkmcnt(0)
	v_mul_f32_e32 v33, v32, v33
	v_cvt_pk_bf16_f32 v33, v33, v109
	v_mul_f32_e32 v28, v32, v28
	ds_write_b16 v128, v33
	s_waitcnt vmcnt(6)
	ds_write_b16 v128, v24 offset:34816
	v_cvt_pk_bf16_f32 v28, v28, v109
	ds_write_b16 v128, v28 offset:272
	ds_write_b16_d16_hi v128, v24 offset:35088
	v_lshlrev_b32_e32 v24, 16, v29
	v_mul_f32_e32 v24, v32, v24
	v_cvt_pk_bf16_f32 v24, v24, v109
	ds_write_b16 v128, v24 offset:544
	ds_write_b16 v128, v25 offset:35360
	v_and_b32_e32 v24, 0xffff0000, v29
	v_mul_f32_e32 v24, v32, v24
	v_cvt_pk_bf16_f32 v24, v24, v109
	ds_write_b16 v128, v24 offset:816
	ds_write_b16_d16_hi v128, v25 offset:35632
	v_lshlrev_b32_e32 v24, 16, v30
	v_mul_f32_e32 v24, v32, v24
	v_cvt_pk_bf16_f32 v24, v24, v109
	ds_write_b16 v128, v24 offset:1088
	ds_write_b16 v128, v26 offset:35904
	v_and_b32_e32 v24, 0xffff0000, v30
	v_mul_f32_e32 v24, v32, v24
	v_cvt_pk_bf16_f32 v24, v24, v109
	ds_write_b16 v128, v24 offset:1360
	ds_write_b16_d16_hi v128, v26 offset:36176
	v_lshlrev_b32_e32 v24, 16, v31
	v_mul_f32_e32 v24, v32, v24
	v_cvt_pk_bf16_f32 v24, v24, v109
	ds_write_b16 v128, v24 offset:1632
	ds_write_b16 v128, v27 offset:36448
	v_and_b32_e32 v24, 0xffff0000, v31
	v_mul_f32_e32 v24, v32, v24
	v_cvt_pk_bf16_f32 v24, v24, v109
	ds_write_b16 v129, v24
	ds_write_b16_d16_hi v129, v27 offset:34816
	ds_read_b32 v24, v126
	s_waitcnt vmcnt(5)
	v_lshlrev_b32_e32 v25, 16, v20
	v_and_b32_e32 v20, 0xffff0000, v20
	s_ashr_i32 s7, s6, 31
	s_lshl_b64 s[20:21], s[6:7], 16
	s_waitcnt lgkmcnt(0)
	v_mul_f32_e32 v25, v24, v25
	v_cvt_pk_bf16_f32 v25, v25, v109
	v_mul_f32_e32 v20, v24, v20
	ds_write_b16 v130, v25
	s_waitcnt vmcnt(4)
	ds_write_b16 v130, v16 offset:34816
	v_cvt_pk_bf16_f32 v20, v20, v109
	ds_write_b16 v130, v20 offset:272
	ds_write_b16_d16_hi v130, v16 offset:35088
	v_lshlrev_b32_e32 v16, 16, v21
	v_mul_f32_e32 v16, v24, v16
	v_cvt_pk_bf16_f32 v16, v16, v109
	ds_write_b16 v130, v16 offset:544
	ds_write_b16 v130, v17 offset:35360
	v_and_b32_e32 v16, 0xffff0000, v21
	v_mul_f32_e32 v16, v24, v16
	v_cvt_pk_bf16_f32 v16, v16, v109
	ds_write_b16 v130, v16 offset:816
	ds_write_b16_d16_hi v130, v17 offset:35632
	v_lshlrev_b32_e32 v16, 16, v22
	v_mul_f32_e32 v16, v24, v16
	v_cvt_pk_bf16_f32 v16, v16, v109
	ds_write_b16 v130, v16 offset:1088
	ds_write_b16 v130, v18 offset:35904
	v_and_b32_e32 v16, 0xffff0000, v22
	v_mul_f32_e32 v16, v24, v16
	v_cvt_pk_bf16_f32 v16, v16, v109
	ds_write_b16 v130, v16 offset:1360
	ds_write_b16_d16_hi v130, v18 offset:36176
	v_lshlrev_b32_e32 v16, 16, v23
	v_mul_f32_e32 v16, v24, v16
	v_cvt_pk_bf16_f32 v16, v16, v109
	ds_write_b16 v130, v16 offset:1632
	ds_write_b16 v130, v19 offset:36448
	v_and_b32_e32 v16, 0xffff0000, v23
	v_mul_f32_e32 v16, v24, v16
	v_cvt_pk_bf16_f32 v16, v16, v109
	ds_write_b16 v131, v16
	ds_write_b16_d16_hi v131, v19 offset:34816
	ds_read_b32 v16, v126
	s_waitcnt vmcnt(3)
	v_lshlrev_b32_e32 v17, 16, v12
	v_and_b32_e32 v12, 0xffff0000, v12
	s_add_u32 s58, s94, s20
	s_addc_u32 s59, s95, s21
	s_waitcnt lgkmcnt(0)
	v_mul_f32_e32 v17, v16, v17
	v_cvt_pk_bf16_f32 v17, v17, v109
	v_mul_f32_e32 v12, v16, v12
	ds_write_b16 v133, v17
	s_waitcnt vmcnt(2)
	ds_write_b16 v133, v8 offset:34816
	v_cvt_pk_bf16_f32 v12, v12, v109
	ds_write_b16 v133, v12 offset:272
	ds_write_b16_d16_hi v133, v8 offset:35088
	v_lshlrev_b32_e32 v8, 16, v13
	v_mul_f32_e32 v8, v16, v8
	v_cvt_pk_bf16_f32 v8, v8, v109
	ds_write_b16 v133, v8 offset:544
	ds_write_b16 v133, v9 offset:35360
	v_and_b32_e32 v8, 0xffff0000, v13
	v_mul_f32_e32 v8, v16, v8
	v_cvt_pk_bf16_f32 v8, v8, v109
	ds_write_b16 v133, v8 offset:816
	ds_write_b16_d16_hi v133, v9 offset:35632
	v_lshlrev_b32_e32 v8, 16, v14
	v_mul_f32_e32 v8, v16, v8
	v_cvt_pk_bf16_f32 v8, v8, v109
	ds_write_b16 v133, v8 offset:1088
	ds_write_b16 v133, v10 offset:35904
	v_and_b32_e32 v8, 0xffff0000, v14
	v_mul_f32_e32 v8, v16, v8
	v_cvt_pk_bf16_f32 v8, v8, v109
	ds_write_b16 v133, v8 offset:1360
	ds_write_b16_d16_hi v133, v10 offset:36176
	v_lshlrev_b32_e32 v8, 16, v15
	v_mul_f32_e32 v8, v16, v8
	v_cvt_pk_bf16_f32 v8, v8, v109
	ds_write_b16 v133, v8 offset:1632
	ds_write_b16 v133, v11 offset:36448
	v_and_b32_e32 v8, 0xffff0000, v15
	v_mul_f32_e32 v8, v16, v8
	v_cvt_pk_bf16_f32 v8, v8, v109
	ds_write_b16 v134, v8
	ds_write_b16_d16_hi v134, v11 offset:34816
	ds_read_b32 v8, v126
	s_waitcnt vmcnt(1)
	v_lshlrev_b32_e32 v9, 16, v4
	v_and_b32_e32 v4, 0xffff0000, v4
	s_waitcnt lgkmcnt(0)
	v_mul_f32_e32 v9, v8, v9
	v_cvt_pk_bf16_f32 v9, v9, v109
	v_mul_f32_e32 v4, v8, v4
	ds_write_b16 v135, v9
	s_waitcnt vmcnt(0)
	ds_write_b16 v135, v0 offset:34816
	v_cvt_pk_bf16_f32 v4, v4, v109
	ds_write_b16 v135, v4 offset:272
	ds_write_b16_d16_hi v135, v0 offset:35088
	v_lshlrev_b32_e32 v0, 16, v5
	v_mul_f32_e32 v0, v8, v0
	v_cvt_pk_bf16_f32 v0, v0, v109
	ds_write_b16 v135, v0 offset:544
	ds_write_b16 v135, v1 offset:35360
	v_and_b32_e32 v0, 0xffff0000, v5
	v_mul_f32_e32 v0, v8, v0
	v_cvt_pk_bf16_f32 v0, v0, v109
	ds_write_b16 v135, v0 offset:816
	ds_write_b16_d16_hi v135, v1 offset:35632
	v_lshlrev_b32_e32 v0, 16, v6
	v_mul_f32_e32 v0, v8, v0
	v_cvt_pk_bf16_f32 v0, v0, v109
	ds_write_b16 v135, v0 offset:1088
	ds_write_b16 v135, v2 offset:35904
	v_and_b32_e32 v0, 0xffff0000, v6
	v_mul_f32_e32 v0, v8, v0
	v_cvt_pk_bf16_f32 v0, v0, v109
	ds_write_b16 v135, v0 offset:1360
	ds_write_b16_d16_hi v135, v2 offset:36176
	v_lshlrev_b32_e32 v0, 16, v7
	v_mul_f32_e32 v0, v8, v0
	v_cvt_pk_bf16_f32 v0, v0, v109
	ds_write_b16 v135, v0 offset:1632
	ds_write_b16 v135, v3 offset:36448
	v_and_b32_e32 v0, 0xffff0000, v7
	v_mul_f32_e32 v0, v8, v0
	v_cvt_pk_bf16_f32 v0, v0, v109
	ds_write_b16 v136, v0
	ds_write_b16_d16_hi v136, v3 offset:34816
	s_waitcnt lgkmcnt(0)
	s_barrier
	ds_read_b128 v[44:47], v127
	ds_read_b128 v[40:43], v127 offset:32
	ds_read_b128 v[36:39], v127 offset:64
	ds_read_b128 v[32:35], v127 offset:96
	ds_read_b128 v[28:31], v127 offset:128
	ds_read_b128 v[24:27], v127 offset:160
	ds_read_b128 v[20:23], v127 offset:192
	ds_read_b128 v[16:19], v127 offset:224
	ds_read_b128 v[0:3], v138 offset:34816
	ds_read_b128 v[160:163], v138 offset:34848
	ds_read_b128 v[164:167], v138 offset:34880
	ds_read_b128 v[168:171], v138 offset:34912
	ds_read_b128 v[172:175], v138 offset:34944
	s_waitcnt lgkmcnt(4)
	v_mfma_f32_32x32x16_bf16 v[0:15], v[0:3], v[44:47], 0
	ds_read_b128 v[176:179], v138 offset:34976
	s_waitcnt lgkmcnt(4)
	v_mfma_f32_32x32x16_bf16 v[0:15], v[160:163], v[40:43], v[0:15]
	ds_read_b128 v[180:183], v138 offset:35008
	s_waitcnt lgkmcnt(4)
	v_mfma_f32_32x32x16_bf16 v[0:15], v[164:167], v[36:39], v[0:15]
	ds_read_b128 v[184:187], v138 offset:35040
	s_waitcnt lgkmcnt(4)
	v_mfma_f32_32x32x16_bf16 v[0:15], v[168:171], v[32:35], v[0:15]
	s_waitcnt lgkmcnt(3)
	v_mfma_f32_32x32x16_bf16 v[0:15], v[172:175], v[28:31], v[0:15]
	s_waitcnt lgkmcnt(2)
	v_mfma_f32_32x32x16_bf16 v[0:15], v[176:179], v[24:27], v[0:15]
	s_waitcnt lgkmcnt(1)
	v_mfma_f32_32x32x16_bf16 v[0:15], v[180:183], v[20:23], v[0:15]
	s_waitcnt lgkmcnt(0)
	v_mfma_f32_32x32x16_bf16 v[0:15], v[184:187], v[16:19], v[0:15]
	v_lshl_add_u64 v[142:143], v[52:53], 2, s[58:59]
	s_nop 10
	global_store_dword v[142:143], v0, off
	v_lshl_add_u64 v[142:143], v[104:105], 2, s[58:59]
	global_store_dword v[142:143], v1, off offset:512
	global_store_dword v[142:143], v2, off offset:1024
	global_store_dword v[142:143], v3, off offset:1536
	v_lshl_add_u64 v[0:1], v[54:55], 2, s[58:59]
	global_store_dword v[0:1], v4, off
	v_lshl_add_u64 v[0:1], v[56:57], 2, s[58:59]
	global_store_dword v[0:1], v5, off
	v_lshl_add_u64 v[0:1], v[58:59], 2, s[58:59]
	global_store_dword v[0:1], v6, off
	v_lshl_add_u64 v[0:1], v[60:61], 2, s[58:59]
	global_store_dword v[0:1], v7, off
	v_lshl_add_u64 v[0:1], v[62:63], 2, s[58:59]
	global_store_dword v[0:1], v8, off
	v_lshl_add_u64 v[0:1], v[64:65], 2, s[58:59]
	global_store_dword v[0:1], v9, off
	v_lshl_add_u64 v[0:1], v[66:67], 2, s[58:59]
	global_store_dword v[0:1], v10, off
	v_lshl_add_u64 v[0:1], v[68:69], 2, s[58:59]
	global_store_dword v[0:1], v11, off
	v_lshl_add_u64 v[0:1], v[70:71], 2, s[58:59]
	global_store_dword v[0:1], v12, off
	v_lshl_add_u64 v[0:1], v[72:73], 2, s[58:59]
	global_store_dword v[0:1], v13, off
	v_lshl_add_u64 v[0:1], v[74:75], 2, s[58:59]
	global_store_dword v[0:1], v14, off
	v_lshl_add_u64 v[0:1], v[76:77], 2, s[58:59]
	global_store_dword v[0:1], v15, off
	ds_read_b128 v[0:3], v139 offset:34816
	ds_read_b128 v[160:163], v139 offset:34848
	ds_read_b128 v[164:167], v139 offset:34880
	ds_read_b128 v[168:171], v139 offset:34912
	ds_read_b128 v[172:175], v139 offset:34944
	s_waitcnt lgkmcnt(4)
	v_mfma_f32_32x32x16_bf16 v[0:15], v[0:3], v[44:47], 0
	ds_read_b128 v[176:179], v139 offset:34976
	s_waitcnt lgkmcnt(4)
	v_mfma_f32_32x32x16_bf16 v[0:15], v[160:163], v[40:43], v[0:15]
	ds_read_b128 v[180:183], v139 offset:35008
	s_waitcnt lgkmcnt(4)
	v_mfma_f32_32x32x16_bf16 v[0:15], v[164:167], v[36:39], v[0:15]
	ds_read_b128 v[184:187], v139 offset:35040
	s_waitcnt lgkmcnt(4)
	v_mfma_f32_32x32x16_bf16 v[0:15], v[168:171], v[32:35], v[0:15]
	s_waitcnt lgkmcnt(3)
	v_mfma_f32_32x32x16_bf16 v[0:15], v[172:175], v[28:31], v[0:15]
	s_waitcnt lgkmcnt(2)
	v_mfma_f32_32x32x16_bf16 v[0:15], v[176:179], v[24:27], v[0:15]
	s_waitcnt lgkmcnt(1)
	v_mfma_f32_32x32x16_bf16 v[0:15], v[180:183], v[20:23], v[0:15]
	s_waitcnt lgkmcnt(0)
	v_mfma_f32_32x32x16_bf16 v[0:15], v[184:187], v[16:19], v[0:15]
	v_lshl_add_u64 v[16:17], v[78:79], 2, s[58:59]
	s_nop 10
	global_store_dword v[16:17], v0, off
	v_lshl_add_u64 v[16:17], v[106:107], 2, s[58:59]
	global_store_dword v[16:17], v1, off offset:512
	global_store_dword v[16:17], v2, off offset:1024
	global_store_dword v[16:17], v3, off offset:1536
	v_lshl_add_u64 v[0:1], v[80:81], 2, s[58:59]
	global_store_dword v[0:1], v4, off
	v_lshl_add_u64 v[0:1], v[82:83], 2, s[58:59]
	global_store_dword v[0:1], v5, off
	v_lshl_add_u64 v[0:1], v[84:85], 2, s[58:59]
	global_store_dword v[0:1], v6, off
	v_lshl_add_u64 v[0:1], v[86:87], 2, s[58:59]
	global_store_dword v[0:1], v7, off
	v_lshl_add_u64 v[0:1], v[88:89], 2, s[58:59]
	global_store_dword v[0:1], v8, off
	v_lshl_add_u64 v[0:1], v[90:91], 2, s[58:59]
	global_store_dword v[0:1], v9, off
	v_lshl_add_u64 v[0:1], v[92:93], 2, s[58:59]
	global_store_dword v[0:1], v10, off
	v_lshl_add_u64 v[0:1], v[94:95], 2, s[58:59]
	global_store_dword v[0:1], v11, off
	v_lshl_add_u64 v[0:1], v[96:97], 2, s[58:59]
	global_store_dword v[0:1], v12, off
	v_lshl_add_u64 v[0:1], v[98:99], 2, s[58:59]
	global_store_dword v[0:1], v13, off
	v_lshl_add_u64 v[0:1], v[100:101], 2, s[58:59]
	global_store_dword v[0:1], v14, off
	v_lshl_add_u64 v[0:1], v[102:103], 2, s[58:59]
	global_store_dword v[0:1], v15, off
	s_and_saveexec_b64 s[58:59], s[8:9]
	s_cbranch_execz .LBB0_4628
	ds_read_b128 v[0:3], v140
	ds_read_b128 v[4:7], v140 offset:16
	ds_read_b128 v[8:11], v140 offset:32
	ds_read_b128 v[12:15], v140 offset:48
	s_lshl_b64 s[6:7], s[6:7], 9
	s_waitcnt lgkmcnt(3)
	v_lshlrev_b32_e32 v16, 16, v0
	v_and_b32_e32 v0, 0xffff0000, v0
	v_add_f32_e32 v16, 0, v16
	v_add_f32_e32 v0, v16, v0
	v_lshlrev_b32_e32 v16, 16, v1
	v_add_f32_e32 v0, v0, v16
	v_and_b32_e32 v1, 0xffff0000, v1
	v_add_f32_e32 v0, v0, v1
	v_lshlrev_b32_e32 v1, 16, v2
	v_add_f32_e32 v0, v0, v1
	v_and_b32_e32 v1, 0xffff0000, v2
	v_add_f32_e32 v0, v0, v1
	v_lshlrev_b32_e32 v1, 16, v3
	v_add_f32_e32 v0, v0, v1
	v_and_b32_e32 v1, 0xffff0000, v3
	v_add_f32_e32 v0, v0, v1
	s_waitcnt lgkmcnt(2)
	v_lshlrev_b32_e32 v1, 16, v4
	v_add_f32_e32 v0, v0, v1
	v_and_b32_e32 v1, 0xffff0000, v4
	v_add_f32_e32 v0, v0, v1
	v_lshlrev_b32_e32 v1, 16, v5
	v_add_f32_e32 v0, v0, v1
	v_and_b32_e32 v1, 0xffff0000, v5
	v_add_f32_e32 v0, v0, v1
	v_lshlrev_b32_e32 v1, 16, v6
	v_add_f32_e32 v0, v0, v1
	v_and_b32_e32 v1, 0xffff0000, v6
	v_add_f32_e32 v0, v0, v1
	v_lshlrev_b32_e32 v1, 16, v7
	v_add_f32_e32 v0, v0, v1
	v_and_b32_e32 v1, 0xffff0000, v7
	v_add_f32_e32 v0, v0, v1
	s_waitcnt lgkmcnt(1)
	v_lshlrev_b32_e32 v1, 16, v8
	v_add_f32_e32 v0, v0, v1
	v_and_b32_e32 v1, 0xffff0000, v8
	v_add_f32_e32 v0, v0, v1
	v_lshlrev_b32_e32 v1, 16, v9
	v_add_f32_e32 v0, v0, v1
	v_and_b32_e32 v1, 0xffff0000, v9
	v_add_f32_e32 v0, v0, v1
	v_lshlrev_b32_e32 v1, 16, v10
	v_add_f32_e32 v0, v0, v1
	v_and_b32_e32 v1, 0xffff0000, v10
	v_add_f32_e32 v0, v0, v1
	v_lshlrev_b32_e32 v1, 16, v11
	v_add_f32_e32 v0, v0, v1
	v_and_b32_e32 v1, 0xffff0000, v11
	v_add_f32_e32 v0, v0, v1
	s_waitcnt lgkmcnt(0)
	v_lshlrev_b32_e32 v1, 16, v12
	v_add_f32_e32 v0, v0, v1
	v_and_b32_e32 v1, 0xffff0000, v12
	v_add_f32_e32 v0, v0, v1
	v_lshlrev_b32_e32 v1, 16, v13
	v_add_f32_e32 v0, v0, v1
	v_and_b32_e32 v1, 0xffff0000, v13
	v_add_f32_e32 v0, v0, v1
	v_lshlrev_b32_e32 v1, 16, v14
	v_add_f32_e32 v0, v0, v1
	v_and_b32_e32 v1, 0xffff0000, v14
	v_add_f32_e32 v4, v0, v1
	ds_read_b128 v[0:3], v140 offset:64
	v_lshlrev_b32_e32 v5, 16, v15
	v_add_f32_e32 v4, v4, v5
	v_and_b32_e32 v5, 0xffff0000, v15
	v_add_f32_e32 v8, v4, v5
	ds_read_b128 v[4:7], v140 offset:80
	s_waitcnt lgkmcnt(1)
	v_lshlrev_b32_e32 v9, 16, v0
	v_add_f32_e32 v8, v8, v9
	v_and_b32_e32 v0, 0xffff0000, v0
	v_add_f32_e32 v0, v8, v0
	v_lshlrev_b32_e32 v8, 16, v1
	v_add_f32_e32 v0, v0, v8
	v_and_b32_e32 v1, 0xffff0000, v1
	v_add_f32_e32 v0, v0, v1
	v_lshlrev_b32_e32 v1, 16, v2
	v_add_f32_e32 v0, v0, v1
	v_and_b32_e32 v1, 0xffff0000, v2
	v_add_f32_e32 v0, v0, v1
	v_lshlrev_b32_e32 v1, 16, v3
	v_add_f32_e32 v0, v0, v1
	v_and_b32_e32 v1, 0xffff0000, v3
	v_add_f32_e32 v0, v0, v1
	s_waitcnt lgkmcnt(0)
	v_lshlrev_b32_e32 v1, 16, v4
	v_add_f32_e32 v0, v0, v1
	v_and_b32_e32 v1, 0xffff0000, v4
	v_add_f32_e32 v0, v0, v1
	v_lshlrev_b32_e32 v1, 16, v5
	v_add_f32_e32 v0, v0, v1
	v_and_b32_e32 v1, 0xffff0000, v5
	v_add_f32_e32 v0, v0, v1
	v_lshlrev_b32_e32 v1, 16, v6
	v_add_f32_e32 v0, v0, v1
	v_and_b32_e32 v1, 0xffff0000, v6
	v_add_f32_e32 v4, v0, v1
	ds_read_b128 v[0:3], v140 offset:96
	v_lshlrev_b32_e32 v5, 16, v7
	v_add_f32_e32 v4, v4, v5
	v_and_b32_e32 v5, 0xffff0000, v7
	v_add_f32_e32 v8, v4, v5
	ds_read_b128 v[4:7], v140 offset:112
	s_waitcnt lgkmcnt(1)
	v_lshlrev_b32_e32 v9, 16, v0
	v_add_f32_e32 v8, v8, v9
	v_and_b32_e32 v0, 0xffff0000, v0
	v_add_f32_e32 v0, v8, v0
	v_lshlrev_b32_e32 v8, 16, v1
	v_add_f32_e32 v0, v0, v8
	v_and_b32_e32 v1, 0xffff0000, v1
	v_add_f32_e32 v0, v0, v1
	v_lshlrev_b32_e32 v1, 16, v2
	v_add_f32_e32 v0, v0, v1
	v_and_b32_e32 v1, 0xffff0000, v2
	v_add_f32_e32 v0, v0, v1
	v_lshlrev_b32_e32 v1, 16, v3
	v_add_f32_e32 v0, v0, v1
	v_and_b32_e32 v1, 0xffff0000, v3
	v_add_f32_e32 v0, v0, v1
	s_waitcnt lgkmcnt(0)
	v_lshlrev_b32_e32 v1, 16, v4
	v_add_f32_e32 v0, v0, v1
	v_and_b32_e32 v1, 0xffff0000, v4
	v_add_f32_e32 v0, v0, v1
	v_lshlrev_b32_e32 v1, 16, v5
	v_add_f32_e32 v0, v0, v1
	v_and_b32_e32 v1, 0xffff0000, v5
	v_add_f32_e32 v0, v0, v1
	v_lshlrev_b32_e32 v1, 16, v6
	v_add_f32_e32 v0, v0, v1
	v_and_b32_e32 v1, 0xffff0000, v6
	v_add_f32_e32 v4, v0, v1
	ds_read_b128 v[0:3], v140 offset:128
	v_lshlrev_b32_e32 v5, 16, v7
	v_add_f32_e32 v4, v4, v5
	v_and_b32_e32 v5, 0xffff0000, v7
	v_add_f32_e32 v8, v4, v5
	ds_read_b128 v[4:7], v140 offset:144
	s_waitcnt lgkmcnt(1)
	v_lshlrev_b32_e32 v9, 16, v0
	v_add_f32_e32 v8, v8, v9
	v_and_b32_e32 v0, 0xffff0000, v0
	v_add_f32_e32 v0, v8, v0
	v_lshlrev_b32_e32 v8, 16, v1
	v_add_f32_e32 v0, v0, v8
	v_and_b32_e32 v1, 0xffff0000, v1
	v_add_f32_e32 v0, v0, v1
	v_lshlrev_b32_e32 v1, 16, v2
	v_add_f32_e32 v0, v0, v1
	v_and_b32_e32 v1, 0xffff0000, v2
	v_add_f32_e32 v0, v0, v1
	v_lshlrev_b32_e32 v1, 16, v3
	v_add_f32_e32 v0, v0, v1
	v_and_b32_e32 v1, 0xffff0000, v3
	v_add_f32_e32 v0, v0, v1
	s_waitcnt lgkmcnt(0)
	v_lshlrev_b32_e32 v1, 16, v4
	v_add_f32_e32 v0, v0, v1
	v_and_b32_e32 v1, 0xffff0000, v4
	v_add_f32_e32 v0, v0, v1
	v_lshlrev_b32_e32 v1, 16, v5
	v_add_f32_e32 v0, v0, v1
	v_and_b32_e32 v1, 0xffff0000, v5
	v_add_f32_e32 v0, v0, v1
	v_lshlrev_b32_e32 v1, 16, v6
	v_add_f32_e32 v0, v0, v1
	v_and_b32_e32 v1, 0xffff0000, v6
	v_add_f32_e32 v4, v0, v1
	ds_read_b128 v[0:3], v140 offset:160
	v_lshlrev_b32_e32 v5, 16, v7
	v_add_f32_e32 v4, v4, v5
	v_and_b32_e32 v5, 0xffff0000, v7
	v_add_f32_e32 v8, v4, v5
	ds_read_b128 v[4:7], v140 offset:176
	s_waitcnt lgkmcnt(1)
	v_lshlrev_b32_e32 v9, 16, v0
	v_add_f32_e32 v8, v8, v9
	v_and_b32_e32 v0, 0xffff0000, v0
	v_add_f32_e32 v0, v8, v0
	v_lshlrev_b32_e32 v8, 16, v1
	v_add_f32_e32 v0, v0, v8
	v_and_b32_e32 v1, 0xffff0000, v1
	v_add_f32_e32 v0, v0, v1
	v_lshlrev_b32_e32 v1, 16, v2
	v_add_f32_e32 v0, v0, v1
	v_and_b32_e32 v1, 0xffff0000, v2
	v_add_f32_e32 v0, v0, v1
	v_lshlrev_b32_e32 v1, 16, v3
	v_add_f32_e32 v0, v0, v1
	v_and_b32_e32 v1, 0xffff0000, v3
	v_add_f32_e32 v0, v0, v1
	s_waitcnt lgkmcnt(0)
	v_lshlrev_b32_e32 v1, 16, v4
	v_add_f32_e32 v0, v0, v1
	v_and_b32_e32 v1, 0xffff0000, v4
	v_add_f32_e32 v0, v0, v1
	v_lshlrev_b32_e32 v1, 16, v5
	v_add_f32_e32 v0, v0, v1
	v_and_b32_e32 v1, 0xffff0000, v5
	v_add_f32_e32 v0, v0, v1
	v_lshlrev_b32_e32 v1, 16, v6
	v_add_f32_e32 v0, v0, v1
	v_and_b32_e32 v1, 0xffff0000, v6
	v_add_f32_e32 v4, v0, v1
	ds_read_b128 v[0:3], v140 offset:192
	v_lshlrev_b32_e32 v5, 16, v7
	v_add_f32_e32 v4, v4, v5
	v_and_b32_e32 v5, 0xffff0000, v7
	v_add_f32_e32 v8, v4, v5
	ds_read_b128 v[4:7], v140 offset:208
	s_waitcnt lgkmcnt(1)
	v_lshlrev_b32_e32 v9, 16, v0
	v_add_f32_e32 v8, v8, v9
	v_and_b32_e32 v0, 0xffff0000, v0
	v_add_f32_e32 v0, v8, v0
	v_lshlrev_b32_e32 v8, 16, v1
	v_add_f32_e32 v0, v0, v8
	v_and_b32_e32 v1, 0xffff0000, v1
	v_add_f32_e32 v0, v0, v1
	v_lshlrev_b32_e32 v1, 16, v2
	v_add_f32_e32 v0, v0, v1
	v_and_b32_e32 v1, 0xffff0000, v2
	v_add_f32_e32 v0, v0, v1
	v_lshlrev_b32_e32 v1, 16, v3
	v_add_f32_e32 v0, v0, v1
	v_and_b32_e32 v1, 0xffff0000, v3
	v_add_f32_e32 v0, v0, v1
	s_waitcnt lgkmcnt(0)
	v_lshlrev_b32_e32 v1, 16, v4
	v_add_f32_e32 v0, v0, v1
	v_and_b32_e32 v1, 0xffff0000, v4
	v_add_f32_e32 v0, v0, v1
	v_lshlrev_b32_e32 v1, 16, v5
	v_add_f32_e32 v0, v0, v1
	v_and_b32_e32 v1, 0xffff0000, v5
	v_add_f32_e32 v0, v0, v1
	v_lshlrev_b32_e32 v1, 16, v6
	v_add_f32_e32 v0, v0, v1
	v_and_b32_e32 v1, 0xffff0000, v6
	v_add_f32_e32 v4, v0, v1
	ds_read_b128 v[0:3], v140 offset:224
	v_lshlrev_b32_e32 v5, 16, v7
	v_add_f32_e32 v4, v4, v5
	v_and_b32_e32 v5, 0xffff0000, v7
	v_add_f32_e32 v8, v4, v5
	ds_read_b128 v[4:7], v140 offset:240
	s_waitcnt lgkmcnt(1)
	v_lshlrev_b32_e32 v9, 16, v0
	v_add_f32_e32 v8, v8, v9
	v_and_b32_e32 v0, 0xffff0000, v0
	v_add_f32_e32 v0, v8, v0
	v_lshlrev_b32_e32 v8, 16, v1
	v_add_f32_e32 v0, v0, v8
	v_and_b32_e32 v1, 0xffff0000, v1
	v_add_f32_e32 v0, v0, v1
	v_lshlrev_b32_e32 v1, 16, v2
	v_add_f32_e32 v0, v0, v1
	v_and_b32_e32 v1, 0xffff0000, v2
	v_add_f32_e32 v0, v0, v1
	v_lshlrev_b32_e32 v1, 16, v3
	v_add_f32_e32 v0, v0, v1
	v_and_b32_e32 v1, 0xffff0000, v3
	v_add_f32_e32 v0, v0, v1
	s_waitcnt lgkmcnt(0)
	v_lshlrev_b32_e32 v1, 16, v4
	v_add_f32_e32 v0, v0, v1
	v_and_b32_e32 v1, 0xffff0000, v4
	v_add_f32_e32 v0, v0, v1
	v_lshlrev_b32_e32 v1, 16, v5
	v_add_f32_e32 v0, v0, v1
	v_and_b32_e32 v1, 0xffff0000, v5
	v_add_f32_e32 v0, v0, v1
	v_lshlrev_b32_e32 v1, 16, v6
	v_add_f32_e32 v0, v0, v1
	v_and_b32_e32 v1, 0xffff0000, v6
	v_add_f32_e32 v0, v0, v1
	v_lshlrev_b32_e32 v1, 16, v7
	v_add_f32_e32 v0, v0, v1
	v_and_b32_e32 v1, 0xffff0000, v7
	v_add_f32_e32 v2, v0, v1
	v_lshl_add_u64 v[0:1], v[50:51], 0, s[6:7]
	global_store_dword v[0:1], v2, off
	s_branch .LBB0_4628

.LBB0_4945:
	s_or_b64 exec, exec, s[6:7]
	v_add_u32_e32 v217, v50, v104
	v_add_u32_e32 v189, 0x11000, v217
	ds_read_b128 v[234:237], v189
	ds_read_b128 v[238:241], v189 offset:32
	v_add_u32_e32 v189, 0x13200, v217
	ds_read_b128 v[242:245], v189
	ds_read_b128 v[246:249], v189 offset:32
	v_add_f32_e32 v45, v51, v52
	v_add_f32_e32 v45, v45, v53
	v_add_f32_e32 v45, v45, v32
	v_add_f32_e32 v45, v45, v34
	v_add_f32_e32 v45, v45, v33
	v_add_f32_e32 v45, v45, v36
	v_add_f32_e32 v45, v45, v35
	v_add_f32_e32 v45, v45, v38
	v_add_f32_e32 v45, v45, v37
	v_add_f32_e32 v45, v45, v40
	v_cvt_pk_bf16_f32 v52, v52, v53
	v_cvt_pk_bf16_f32 v53, v32, v34
	v_cvt_pk_bf16_f32 v54, v33, v36
	v_cvt_pk_bf16_f32 v55, v35, v38
	v_cvt_pk_bf16_f32 v32, v37, v40
	v_add_u32_e32 v40, v50, v104
	v_add_f32_e32 v45, v45, v39
	v_permlane32_swap_b32_e32 v52, v54
	v_permlane32_swap_b32_e32 v53, v55
	v_cvt_pk_bf16_f32 v33, v39, v42
	v_cvt_pk_bf16_f32 v34, v41, v56
	v_cvt_pk_bf16_f32 v35, v44, v43
	s_waitcnt lgkmcnt(3)
	v_mfma_f32_32x32x16_bf16 v[16:31], v[52:55], v[234:237], v[16:31]
	v_permlane32_swap_b32_e32 v32, v34
	v_permlane32_swap_b32_e32 v33, v35
	v_add_f32_e32 v45, v45, v42
	s_waitcnt lgkmcnt(2)
	v_mfma_f32_32x32x16_bf16 v[16:31], v[32:35], v[238:241], v[16:31]
	v_add_f32_e32 v45, v45, v41
	v_add_f32_e32 v45, v45, v56
	v_add_f32_e32 v45, v45, v44
	s_add_i32 s9, s9, 32
	s_addk_i32 s8, 0x80
	s_waitcnt lgkmcnt(1)
	v_mfma_f32_32x32x16_bf16 v[0:15], v[52:55], v[242:245], v[0:15]
	v_add_f32_e32 v51, v45, v43
	v_add_u32_e32 v50, 64, v50
	v_add_u32_e32 v49, 0x2200, v49
	s_cmp_eq_u32 s10, s9
	s_waitcnt lgkmcnt(0)
	v_mfma_f32_32x32x16_bf16 v[0:15], v[32:35], v[246:249], v[0:15]
	s_cbranch_scc1 .LBB0_4978
